# gla_o reads its once-used f32 chunk states and q/r tiles with the nt hint so they displace less of the Z stream the apply is about to read
# speedup vs baseline: 1.0109x; 1.0071x over previous
.LBB0_839:
	s_or_b64 exec, exec, s[10:11]
	v_lshl_add_u64 v[0:1], s[0:1], 0, v[40:41]
	v_mov_b64_e32 v[2:3], s[44:45]
	v_mad_u64_u32 v[2:3], s[0:1], v0, s17, v[2:3]
	v_mov_b32_e32 v4, v3
	v_mad_u64_u32 v[4:5], s[0:1], v1, s17, v[4:5]
	v_mov_b32_e32 v3, v4
	s_lshl_b32 s4, s22, 9
	v_lshl_add_u64 v[2:3], v[2:3], 0, s[4:5]
	v_lshl_add_u64 v[2:3], v[2:3], 0, v[34:35]
	v_add_co_u32_e64 v4, s[0:1], s19, v2
	s_waitcnt lgkmcnt(0)
	s_barrier
	global_load_dwordx4 v[6:9], v[42:43], off offset:16 nt
	global_load_dwordx4 v[10:13], v[42:43], off nt
	v_addc_co_u32_e64 v5, s[0:1], 0, v3, s[0:1]
	global_load_dwordx4 v[14:17], v[4:5], off nt
	v_lshlrev_b64 v[0:1], 11, v[0:1]
	v_lshl_add_u64 v[0:1], s[6:7], 0, v[0:1]
	ds_read2st64_b32 v[4:5], v75 offset1:1
	ds_read2st64_b32 v[26:27], v75 offset0:2 offset1:3
	ds_read2st64_b32 v[28:29], v75 offset0:4 offset1:5
	ds_read2st64_b32 v[30:31], v75 offset0:6 offset1:7
	ds_read_b128 v[18:21], v76
	ds_read_b128 v[22:25], v76 offset:16
	v_lshl_add_u64 v[86:87], v[0:1], 0, s[4:5]
	s_waitcnt lgkmcnt(5)
	v_add_f32_e32 v0, 0, v4
	v_add_f32_e32 v0, v0, v5
	s_waitcnt lgkmcnt(4)
	v_add_f32_e32 v0, v0, v26
	v_add_f32_e32 v0, v0, v27
	s_waitcnt lgkmcnt(3)
	v_add_f32_e32 v0, v0, v28
	v_add_f32_e32 v0, v0, v29
	s_waitcnt lgkmcnt(2)
	v_add_f32_e32 v0, v0, v30
	v_add_f32_e32 v0, v0, v31
	v_fmamk_f32 v0, v0, 0x3b800000, v84
	v_mul_f32_e32 v1, 0x4b800000, v0
	v_cmp_gt_f32_e64 s[0:1], s18, v0
	v_lshl_add_u64 v[30:31], v[2:3], 0, s[14:15]
	s_add_i32 s21, s30, s21
	v_cndmask_b32_e64 v0, v0, v1, s[0:1]
	v_rsq_f32_e32 v4, v0
	global_load_dwordx4 v[26:29], v[30:31], off offset:128 nt
	global_load_dwordx4 v[0:3], v[30:31], off offset:384 nt
	s_cmpk_gt_i32 s21, 0x1ff
	v_lshl_add_u64 v[46:47], v[46:47], 0, s[8:9]
	v_mul_f32_e32 v5, 0x45800000, v4
	v_cndmask_b32_e64 v4, v4, v5, s[0:1]
	s_waitcnt vmcnt(4) lgkmcnt(0)
	v_pk_mul_f32 v[8:9], v[24:25], v[8:9]
	s_waitcnt vmcnt(3)
	v_pk_mul_f32 v[12:13], v[20:21], v[12:13]
	v_pk_mul_f32 v[10:11], v[18:19], v[10:11]
	v_pk_mul_f32 v[6:7], v[22:23], v[6:7]
	v_mov_b32_e32 v18, v10
	v_mov_b32_e32 v19, v12
	v_mov_b32_e32 v12, v11
	v_mov_b32_e32 v10, v6
	v_mov_b32_e32 v11, v8
	v_mov_b32_e32 v8, v7
	s_waitcnt vmcnt(2)
	v_lshlrev_b32_e32 v7, 16, v15
	v_lshlrev_b32_e32 v6, 16, v14
	v_and_b32_e32 v15, 0xffff0000, v15
	v_and_b32_e32 v14, 0xffff0000, v14
	v_lshlrev_b32_e32 v20, 16, v16
	v_mul_f32_e32 v5, 0xbfb8aa3b, v6
	v_mul_f32_e32 v22, 0xbfb8aa3b, v14
	v_mul_f32_e32 v23, 0xbfb8aa3b, v7
	v_mul_f32_e32 v24, 0xbfb8aa3b, v15
	v_mul_f32_e32 v25, 0xbfb8aa3b, v20
	v_exp_f32_e32 v5, v5
	v_exp_f32_e32 v22, v22
	v_exp_f32_e32 v23, v23
	v_exp_f32_e32 v24, v24
	v_exp_f32_e32 v25, v25
	v_lshlrev_b32_e32 v21, 16, v17
	v_and_b32_e32 v17, 0xffff0000, v17
	v_and_b32_e32 v16, 0xffff0000, v16
	v_mul_f32_e32 v89, 0xbfb8aa3b, v21
	v_mul_f32_e32 v90, 0xbfb8aa3b, v17
	v_mul_f32_e32 v88, 0xbfb8aa3b, v16
	v_exp_f32_e32 v89, v89
	v_exp_f32_e32 v91, v90
	v_add_f32_e32 v5, 1.0, v5
	v_add_f32_e32 v90, 1.0, v22
	v_add_f32_e32 v23, 1.0, v23
	v_add_f32_e32 v92, 1.0, v24
	v_exp_f32_e32 v88, v88
	v_add_f32_e32 v93, 1.0, v25
	v_rcp_f32_e32 v22, v5
	v_rcp_f32_e32 v24, v90
	v_rcp_f32_e32 v23, v23
	v_rcp_f32_e32 v25, v92
	v_add_f32_e32 v89, 1.0, v89
	v_add_f32_e32 v94, 1.0, v88
	v_rcp_f32_e32 v88, v93
	v_rcp_f32_e32 v89, v89
	v_pk_mul_f32 v[6:7], v[22:23], v[6:7]
	v_pk_mul_f32 v[14:15], v[24:25], v[14:15]
	v_pk_mul_f32 v[6:7], v[4:5], v[6:7] op_sel_hi:[0,1]
	v_pk_mul_f32 v[14:15], v[4:5], v[14:15] op_sel_hi:[0,1]
	v_add_f32_e32 v5, 1.0, v91
	v_rcp_f32_e32 v90, v94
	v_rcp_f32_e32 v91, v5
	v_pk_mul_f32 v[12:13], v[12:13], v[14:15]
	v_pk_mul_f32 v[14:15], v[88:89], v[20:21]
	v_pk_mul_f32 v[6:7], v[18:19], v[6:7]
	v_pk_mul_f32 v[14:15], v[4:5], v[14:15] op_sel_hi:[0,1]
	v_pk_mul_f32 v[10:11], v[10:11], v[14:15]
	v_pk_mul_f32 v[14:15], v[90:91], v[16:17]
	v_bfe_u32 v16, v12, 16, 1
	v_pk_mul_f32 v[14:15], v[4:5], v[14:15] op_sel_hi:[0,1]
	v_pk_mul_f32 v[8:9], v[8:9], v[14:15]
	v_bfe_u32 v15, v13, 16, 1
	v_bfe_u32 v5, v9, 16, 1
	v_bfe_u32 v14, v8, 16, 1
	v_add3_u32 v12, v12, v16, s16
	v_add3_u32 v13, v13, v15, s16
	v_add3_u32 v8, v8, v14, s16
	v_add3_u32 v5, v9, v5, s16
	v_bfe_u32 v9, v6, 16, 1
	v_bfe_u32 v14, v7, 16, 1
	v_bfe_u32 v15, v10, 16, 1
	v_bfe_u32 v16, v11, 16, 1
	v_add3_u32 v11, v11, v16, s16
	v_add3_u32 v10, v10, v15, s16
	v_add3_u32 v7, v7, v14, s16
	v_add3_u32 v6, v6, v9, s16
	v_lshrrev_b32_e32 v6, 16, v6
	v_lshrrev_b32_e32 v7, 16, v7
	v_lshrrev_b32_e32 v9, 16, v10
	v_lshrrev_b32_e32 v10, 16, v11
	v_and_or_b32 v11, v5, s20, v10
	v_and_or_b32 v10, v8, s20, v9
	v_and_or_b32 v9, v13, s20, v7
	v_and_or_b32 v8, v12, s20, v6
	v_lshl_add_u64 v[6:7], v[86:87], 0, v[34:35]
	global_store_dwordx4 v[6:7], v[8:11], off
	global_load_dwordx4 v[8:11], v[42:43], off offset:256 nt
	s_nop 0
	global_load_dwordx4 v[12:15], v[42:43], off offset:272 nt
	s_waitcnt vmcnt(4)
	v_lshlrev_b32_e32 v25, 16, v27
	v_lshlrev_b32_e32 v24, 16, v26
	v_and_b32_e32 v26, 0xffff0000, v26
	v_mul_f32_e32 v5, 0xbfb8aa3b, v24
	v_mul_f32_e32 v91, 0xbfb8aa3b, v25
	v_mul_f32_e32 v90, 0xbfb8aa3b, v26
	v_exp_f32_e32 v5, v5
	v_exp_f32_e32 v91, v91
	v_exp_f32_e32 v90, v90
	ds_read_b128 v[16:19], v76 offset:256
	ds_read_b128 v[20:23], v76 offset:272
	global_load_dwordx4 v[86:89], v[30:31], off offset:256 nt
	v_lshlrev_b32_e32 v30, 16, v28
	v_and_b32_e32 v28, 0xffff0000, v28
	v_and_b32_e32 v27, 0xffff0000, v27
	v_mul_f32_e32 v94, 0xbfb8aa3b, v28
	v_add_f32_e32 v5, 1.0, v5
	v_add_f32_e32 v91, 1.0, v91
	v_mul_f32_e32 v92, 0xbfb8aa3b, v27
	v_exp_f32_e32 v94, v94
	v_add_f32_e32 v96, 1.0, v90
	v_rcp_f32_e32 v90, v5
	v_rcp_f32_e32 v91, v91
	v_mul_f32_e32 v93, 0xbfb8aa3b, v30
	v_exp_f32_e32 v92, v92
	v_exp_f32_e32 v93, v93
	v_lshlrev_b32_e32 v31, 16, v29
	v_add_f32_e32 v5, 1.0, v94
	v_pk_mul_f32 v[24:25], v[90:91], v[24:25]
	v_and_b32_e32 v29, 0xffff0000, v29
	v_mul_f32_e32 v95, 0xbfb8aa3b, v31
	v_add_f32_e32 v97, 1.0, v92
	v_pk_mul_f32 v[24:25], v[4:5], v[24:25] op_sel_hi:[0,1]
	v_exp_f32_e32 v95, v95
	v_add_f32_e32 v98, 1.0, v93
	v_rcp_f32_e32 v92, v96
	v_rcp_f32_e32 v93, v97
	v_rcp_f32_e32 v94, v98
	v_pk_mul_f32 v[26:27], v[92:93], v[26:27]
	s_nop 0
	v_pk_mul_f32 v[26:27], v[4:5], v[26:27] op_sel_hi:[0,1]
	s_waitcnt vmcnt(2) lgkmcnt(1)
	v_pk_mul_f32 v[10:11], v[18:19], v[10:11]
	v_pk_mul_f32 v[8:9], v[16:17], v[8:9]
	s_waitcnt vmcnt(1) lgkmcnt(0)
	v_pk_mul_f32 v[14:15], v[22:23], v[14:15]
	v_pk_mul_f32 v[12:13], v[20:21], v[12:13]
	v_mov_b32_e32 v16, v8
	v_mov_b32_e32 v17, v10
	v_mov_b32_e32 v10, v9
	v_mov_b32_e32 v8, v12
	v_mov_b32_e32 v9, v14
	v_mov_b32_e32 v14, v13
	v_pk_mul_f32 v[12:13], v[24:25], v[16:17]
	v_mul_f32_e32 v16, 0xbfb8aa3b, v29
	v_exp_f32_e32 v17, v16
	v_add_f32_e32 v16, 1.0, v95
	v_rcp_f32_e32 v95, v16
	v_rcp_f32_e32 v16, v5
	v_add_f32_e32 v5, 1.0, v17
	v_rcp_f32_e32 v17, v5
	v_pk_mul_f32 v[18:19], v[94:95], v[30:31]
	v_pk_mul_f32 v[10:11], v[26:27], v[10:11]
	v_pk_mul_f32 v[18:19], v[4:5], v[18:19] op_sel_hi:[0,1]
	v_pk_mul_f32 v[16:17], v[16:17], v[28:29]
	v_pk_mul_f32 v[8:9], v[18:19], v[8:9]
	v_pk_mul_f32 v[16:17], v[4:5], v[16:17] op_sel_hi:[0,1]
	v_pk_mul_f32 v[14:15], v[16:17], v[14:15]
	v_bfe_u32 v17, v11, 16, 1
	v_bfe_u32 v5, v15, 16, 1
	v_bfe_u32 v16, v14, 16, 1
	v_bfe_u32 v18, v10, 16, 1
	v_add3_u32 v18, v10, v18, s16
	v_add3_u32 v17, v11, v17, s16
	v_add3_u32 v10, v14, v16, s16
	v_add3_u32 v5, v15, v5, s16
	v_bfe_u32 v11, v12, 16, 1
	v_bfe_u32 v14, v13, 16, 1
	v_bfe_u32 v15, v8, 16, 1
	v_bfe_u32 v16, v9, 16, 1
	v_add3_u32 v9, v9, v16, s16
	v_add3_u32 v8, v8, v15, s16
	v_add3_u32 v13, v13, v14, s16
	v_add3_u32 v11, v12, v11, s16
	v_lshrrev_b32_e32 v12, 16, v11
	v_lshrrev_b32_e32 v13, 16, v13
	v_lshrrev_b32_e32 v8, 16, v8
	v_lshrrev_b32_e32 v9, 16, v9
	v_and_or_b32 v11, v5, s20, v9
	v_and_or_b32 v10, v10, s20, v8
	v_and_or_b32 v9, v17, s20, v13
	v_and_or_b32 v8, v18, s20, v12
	global_store_dwordx4 v[6:7], v[8:11], off offset:128
	global_load_dwordx4 v[8:11], v[42:43], off offset:512 nt
	s_nop 0
	global_load_dwordx4 v[12:15], v[42:43], off offset:528 nt
	s_waitcnt vmcnt(3)
	v_lshlrev_b32_e32 v25, 16, v87
	v_lshlrev_b32_e32 v24, 16, v86
	v_and_b32_e32 v27, 0xffff0000, v87
	v_and_b32_e32 v26, 0xffff0000, v86
	v_lshlrev_b32_e32 v28, 16, v88
	v_and_b32_e32 v30, 0xffff0000, v88
	v_mul_f32_e32 v5, 0xbfb8aa3b, v24
	v_mul_f32_e32 v86, 0xbfb8aa3b, v26
	v_mul_f32_e32 v87, 0xbfb8aa3b, v25
	v_mul_f32_e32 v88, 0xbfb8aa3b, v27
	v_exp_f32_e32 v5, v5
	v_exp_f32_e32 v86, v86
	v_exp_f32_e32 v87, v87
	v_exp_f32_e32 v88, v88
	v_lshlrev_b32_e32 v29, 16, v89
	v_and_b32_e32 v31, 0xffff0000, v89
	v_mul_f32_e32 v89, 0xbfb8aa3b, v28
	v_mul_f32_e32 v90, 0xbfb8aa3b, v30
	v_exp_f32_e32 v91, v89
	v_exp_f32_e32 v92, v90
	v_add_f32_e32 v5, 1.0, v5
	v_add_f32_e32 v89, 1.0, v86
	v_add_f32_e32 v87, 1.0, v87
	v_add_f32_e32 v90, 1.0, v88
	ds_read_b128 v[16:19], v76 offset:512
	ds_read_b128 v[20:23], v76 offset:528
	v_rcp_f32_e32 v86, v5
	v_rcp_f32_e32 v88, v89
	v_rcp_f32_e32 v87, v87
	v_rcp_f32_e32 v89, v90
	v_add_f32_e32 v5, 1.0, v91
	v_rcp_f32_e32 v90, v5
	v_pk_mul_f32 v[24:25], v[86:87], v[24:25]
	v_pk_mul_f32 v[26:27], v[88:89], v[26:27]
	v_pk_mul_f32 v[24:25], v[4:5], v[24:25] op_sel_hi:[0,1]
	v_pk_mul_f32 v[26:27], v[4:5], v[26:27] op_sel_hi:[0,1]
	v_mul_f32_e32 v5, 0xbfb8aa3b, v29
	v_exp_f32_e32 v5, v5
	s_waitcnt vmcnt(1) lgkmcnt(1)
	v_pk_mul_f32 v[10:11], v[18:19], v[10:11]
	v_pk_mul_f32 v[8:9], v[16:17], v[8:9]
	s_waitcnt vmcnt(0) lgkmcnt(0)
	v_pk_mul_f32 v[14:15], v[22:23], v[14:15]
	v_pk_mul_f32 v[12:13], v[20:21], v[12:13]
	v_mov_b32_e32 v16, v8
	v_mov_b32_e32 v17, v10
	v_mov_b32_e32 v10, v9
	v_mov_b32_e32 v8, v12
	v_mov_b32_e32 v9, v14
	v_mov_b32_e32 v14, v13
	v_pk_mul_f32 v[12:13], v[24:25], v[16:17]
	v_mul_f32_e32 v17, 0xbfb8aa3b, v31
	v_exp_f32_e32 v17, v17
	v_add_f32_e32 v5, 1.0, v5
	v_add_f32_e32 v16, 1.0, v92
	v_rcp_f32_e32 v91, v5
	v_add_f32_e32 v5, 1.0, v17
	v_rcp_f32_e32 v16, v16
	v_rcp_f32_e32 v17, v5
	v_pk_mul_f32 v[18:19], v[90:91], v[28:29]
	v_pk_mul_f32 v[10:11], v[26:27], v[10:11]
	v_pk_mul_f32 v[18:19], v[4:5], v[18:19] op_sel_hi:[0,1]
	v_pk_mul_f32 v[16:17], v[16:17], v[30:31]
	v_pk_mul_f32 v[8:9], v[18:19], v[8:9]
	v_pk_mul_f32 v[16:17], v[4:5], v[16:17] op_sel_hi:[0,1]
	v_pk_mul_f32 v[14:15], v[16:17], v[14:15]
	v_bfe_u32 v17, v11, 16, 1
	v_bfe_u32 v5, v15, 16, 1
	v_bfe_u32 v16, v14, 16, 1
	v_bfe_u32 v18, v10, 16, 1
	v_add3_u32 v18, v10, v18, s16
	v_add3_u32 v17, v11, v17, s16
	v_add3_u32 v10, v14, v16, s16
	v_add3_u32 v5, v15, v5, s16
	v_bfe_u32 v11, v12, 16, 1
	v_bfe_u32 v14, v13, 16, 1
	v_bfe_u32 v15, v8, 16, 1
	v_bfe_u32 v16, v9, 16, 1
	v_add3_u32 v9, v9, v16, s16
	v_add3_u32 v8, v8, v15, s16
	v_add3_u32 v13, v13, v14, s16
	v_add3_u32 v11, v12, v11, s16
	v_lshrrev_b32_e32 v12, 16, v11
	v_lshrrev_b32_e32 v13, 16, v13
	v_lshrrev_b32_e32 v8, 16, v8
	v_lshrrev_b32_e32 v9, 16, v9
	v_and_or_b32 v11, v5, s20, v9
	v_and_or_b32 v10, v10, s20, v8
	v_and_or_b32 v9, v17, s20, v13
	v_and_or_b32 v8, v18, s20, v12
	global_store_dwordx4 v[6:7], v[8:11], off offset:256
	global_load_dwordx4 v[8:11], v[42:43], off offset:768 nt
	s_nop 0
	global_load_dwordx4 v[12:15], v[42:43], off offset:784 nt
	v_lshlrev_b32_e32 v25, 16, v1
	v_lshlrev_b32_e32 v24, 16, v0
	v_and_b32_e32 v1, 0xffff0000, v1
	v_and_b32_e32 v0, 0xffff0000, v0
	v_mul_f32_e32 v28, 0xbfb8aa3b, v0
	v_mul_f32_e32 v30, 0xbfb8aa3b, v1
	v_exp_f32_e32 v28, v28
	v_exp_f32_e32 v30, v30
	v_lshlrev_b32_e32 v26, 16, v2
	v_mul_f32_e32 v5, 0xbfb8aa3b, v24
	v_mul_f32_e32 v31, 0xbfb8aa3b, v26
	v_mul_f32_e32 v29, 0xbfb8aa3b, v25
	v_exp_f32_e32 v5, v5
	v_exp_f32_e32 v86, v31
	v_add_f32_e32 v31, 1.0, v28
	v_add_f32_e32 v87, 1.0, v30
	ds_read_b128 v[16:19], v76 offset:768
	ds_read_b128 v[20:23], v76 offset:784
	v_exp_f32_e32 v29, v29
	v_rcp_f32_e32 v30, v31
	v_rcp_f32_e32 v31, v87
	v_add_f32_e32 v5, 1.0, v5
	v_add_f32_e32 v29, 1.0, v29
	v_rcp_f32_e32 v28, v5
	v_add_f32_e32 v5, 1.0, v86
	v_pk_mul_f32 v[0:1], v[30:31], v[0:1]
	v_rcp_f32_e32 v29, v29
	v_and_b32_e32 v2, 0xffff0000, v2
	v_pk_mul_f32 v[0:1], v[4:5], v[0:1] op_sel_hi:[0,1]
	v_lshlrev_b32_e32 v27, 16, v3
	v_pk_mul_f32 v[24:25], v[28:29], v[24:25]
	v_and_b32_e32 v3, 0xffff0000, v3
	v_pk_mul_f32 v[24:25], v[4:5], v[24:25] op_sel_hi:[0,1]
	s_waitcnt vmcnt(1) lgkmcnt(1)
	v_pk_mul_f32 v[10:11], v[18:19], v[10:11]
	v_pk_mul_f32 v[8:9], v[16:17], v[8:9]
	v_mov_b32_e32 v17, v10
	v_mov_b32_e32 v10, v9
	v_pk_mul_f32 v[0:1], v[0:1], v[10:11]
	v_mul_f32_e32 v10, 0xbfb8aa3b, v2
	v_exp_f32_e32 v11, v10
	s_waitcnt vmcnt(0) lgkmcnt(0)
	v_pk_mul_f32 v[14:15], v[22:23], v[14:15]
	v_pk_mul_f32 v[12:13], v[20:21], v[12:13]
	v_mov_b32_e32 v16, v8
	v_rcp_f32_e32 v10, v5
	v_mul_f32_e32 v5, 0xbfb8aa3b, v27
	v_mov_b32_e32 v8, v12
	v_mov_b32_e32 v9, v14
	v_mov_b32_e32 v14, v13
	v_pk_mul_f32 v[12:13], v[24:25], v[16:17]
	v_exp_f32_e32 v5, v5
	v_add_f32_e32 v16, 1.0, v11
	v_mul_f32_e32 v11, 0xbfb8aa3b, v3
	v_exp_f32_e32 v17, v11
	v_add_f32_e32 v5, 1.0, v5
	v_rcp_f32_e32 v11, v5
	v_rcp_f32_e32 v16, v16
	v_add_f32_e32 v5, 1.0, v17
	v_rcp_f32_e32 v17, v5
	v_pk_mul_f32 v[10:11], v[10:11], v[26:27]
	v_pk_mul_f32 v[2:3], v[16:17], v[2:3]
	s_nop 0
	v_pk_mul_f32 v[2:3], v[4:5], v[2:3] op_sel_hi:[0,1]
	v_pk_mul_f32 v[10:11], v[4:5], v[10:11] op_sel_hi:[0,1]
	v_pk_mul_f32 v[2:3], v[2:3], v[14:15]
	v_pk_mul_f32 v[8:9], v[10:11], v[8:9]
	v_bfe_u32 v4, v3, 16, 1
	v_bfe_u32 v5, v2, 16, 1
	v_bfe_u32 v10, v1, 16, 1
	v_bfe_u32 v11, v0, 16, 1
	v_add3_u32 v0, v0, v11, s16
	v_add3_u32 v1, v1, v10, s16
	v_add3_u32 v2, v2, v5, s16
	v_add3_u32 v3, v3, v4, s16
	v_bfe_u32 v4, v12, 16, 1
	v_bfe_u32 v5, v13, 16, 1
	v_bfe_u32 v10, v8, 16, 1
	v_bfe_u32 v11, v9, 16, 1
	v_add3_u32 v9, v9, v11, s16
	v_add3_u32 v8, v8, v10, s16
	v_add3_u32 v5, v13, v5, s16
	v_add3_u32 v4, v12, v4, s16
	v_lshrrev_b32_e32 v4, 16, v4
	v_lshrrev_b32_e32 v5, 16, v5
	v_lshrrev_b32_e32 v8, 16, v8
	v_lshrrev_b32_e32 v9, 16, v9
	v_and_or_b32 v3, v3, s20, v9
	v_and_or_b32 v2, v2, s20, v8
	v_and_or_b32 v1, v1, s20, v5
	v_and_or_b32 v0, v0, s20, v4
	global_store_dwordx4 v[6:7], v[0:3], off offset:384
	s_barrier
	s_cbranch_scc1 .LBB0_874

.LBB0_841:
	v_lshl_add_u64 v[2:3], v[0:1], 0, v[52:53]
	v_lshl_add_u64 v[6:7], v[0:1], 0, v[48:49]
	v_lshl_add_u64 v[10:11], v[0:1], 0, v[50:51]
	s_waitcnt vmcnt(0)
	v_lshl_add_u64 v[14:15], v[0:1], 0, v[44:45]
	global_load_dwordx4 v[2:5], v[2:3], off nt
	s_nop 0
	global_load_dwordx4 v[6:9], v[6:7], off nt
	s_nop 0
	global_load_dwordx4 v[10:13], v[10:11], off nt
	s_nop 0
	global_load_dwordx4 v[14:17], v[14:15], off nt
	v_add_u32_e32 v18, s0, v79
	v_add_u32_e32 v19, s0, v78
	v_add_u32_e32 v20, s0, v77
	s_add_i32 s0, s0, 16
	v_lshl_add_u64 v[0:1], v[0:1], 0, s[12:13]
	v_mad_u32_u24 v21, v18, s3, v33
	v_add_u32_e32 v18, 8, v18
	s_cmp_eq_u32 s0, 64
	v_mad_u32_u24 v19, v19, s3, v33
	v_mad_u32_u24 v20, v20, s3, v33
	v_mad_u32_u24 v18, v18, s3, v33
	s_waitcnt vmcnt(3)
	v_bfe_u32 v22, v2, 16, 1
	v_bfe_u32 v23, v3, 16, 1
	v_bfe_u32 v24, v4, 16, 1
	v_bfe_u32 v25, v5, 16, 1
	s_waitcnt vmcnt(2)
	v_bfe_u32 v26, v6, 16, 1
	v_bfe_u32 v27, v7, 16, 1
	v_bfe_u32 v28, v8, 16, 1
	v_bfe_u32 v29, v9, 16, 1
	s_waitcnt vmcnt(1)
	v_bfe_u32 v30, v10, 16, 1
	v_bfe_u32 v31, v11, 16, 1
	v_bfe_u32 v86, v12, 16, 1
	v_bfe_u32 v87, v13, 16, 1
	s_waitcnt vmcnt(0)
	v_bfe_u32 v88, v14, 16, 1
	v_bfe_u32 v89, v15, 16, 1
	v_bfe_u32 v90, v16, 16, 1
	v_bfe_u32 v91, v17, 16, 1
	v_add3_u32 v2, v2, v22, s16
	v_add3_u32 v3, v3, v23, s16
	v_add3_u32 v4, v4, v24, s16
	v_add3_u32 v5, v5, v25, s16
	v_add3_u32 v6, v6, v26, s16
	v_add3_u32 v7, v7, v27, s16
	v_add3_u32 v8, v8, v28, s16
	v_add3_u32 v9, v9, v29, s16
	v_add3_u32 v10, v10, v30, s16
	v_add3_u32 v11, v11, v31, s16
	v_add3_u32 v12, v12, v86, s16
	v_add3_u32 v13, v13, v87, s16
	v_add3_u32 v14, v14, v88, s16
	v_add3_u32 v15, v15, v89, s16
	v_add3_u32 v16, v16, v90, s16
	v_add3_u32 v17, v17, v91, s16
	ds_write_b16_d16_hi v21, v2
	ds_write_b16_d16_hi v21, v3 offset:272
	ds_write_b16_d16_hi v21, v4 offset:544
	ds_write_b16_d16_hi v21, v5 offset:816
	ds_write_b16_d16_hi v19, v6
	ds_write_b16_d16_hi v19, v7 offset:272
	ds_write_b16_d16_hi v19, v8 offset:544
	ds_write_b16_d16_hi v19, v9 offset:816
	ds_write_b16_d16_hi v18, v10
	ds_write_b16_d16_hi v18, v11 offset:272
	ds_write_b16_d16_hi v18, v12 offset:544
	ds_write_b16_d16_hi v18, v13 offset:816
	ds_write_b16_d16_hi v20, v14
	ds_write_b16_d16_hi v20, v15 offset:272
	ds_write_b16_d16_hi v20, v16 offset:544
	ds_write_b16_d16_hi v20, v17 offset:816
	s_cbranch_scc0 .LBB0_841
	s_lshl_b32 s0, s21, 4
	s_and_b32 s4, s0, 0xfc0
	s_ashr_i32 s0, s21, 8
	s_ashr_i32 s1, s0, 31
	s_and_b32 s22, s21, 3
	s_lshl_b64 s[0:1], s[0:1], 12
	s_or_b32 s0, s0, s4
	s_lshl_b32 s4, s22, 8
	v_lshl_add_u64 v[0:1], v[36:37], 0, s[4:5]
	v_or_b32_e32 v2, s0, v32
	v_lshl_add_u64 v[4:5], s[0:1], 0, v[38:39]
	v_mad_u64_u32 v[2:3], s[10:11], v2, s17, v[0:1]
	v_mad_u64_u32 v[6:7], s[10:11], v4, s17, v[0:1]
	v_mad_i32_i24 v3, s1, v85, v3
	v_mad_i32_i24 v7, v5, s17, v7
	global_load_dwordx4 v[0:3], v[2:3], off nt
	s_nop 0
	global_load_dwordx4 v[4:7], v[6:7], off nt
	s_waitcnt vmcnt(1)
	ds_write_b128 v80, v[0:3]
	s_waitcnt vmcnt(0)
	ds_write_b128 v81, v[4:7]
	s_waitcnt lgkmcnt(0)
	s_barrier
	ds_read_b128 v[0:3], v83
	ds_read_b128 v[4:7], v82
	ds_read_b128 v[8:11], v82 offset:64
	ds_read_b128 v[12:15], v83 offset:64
	ds_read_b128 v[20:23], v82 offset:4352
	ds_read_b128 v[24:27], v82 offset:4416
	ds_read_b128 v[28:31], v83 offset:4352
	ds_read_b128 v[86:89], v83 offset:4416
	ds_read_b128 v[94:97], v83 offset:8704
	ds_read_b128 v[98:101], v83 offset:8768
	ds_read_b128 v[106:109], v83 offset:13056
	ds_read_b128 v[110:113], v83 offset:13120
	s_waitcnt lgkmcnt(10)
	v_mfma_f32_16x16x32_bf16 v[16:19], v[0:3], v[4:7], 0
	s_waitcnt lgkmcnt(7)
	v_mfma_f32_16x16x32_bf16 v[0:3], v[0:3], v[20:23], 0
	s_waitcnt lgkmcnt(5)
	v_mfma_f32_16x16x32_bf16 v[90:93], v[28:31], v[4:7], 0
	v_mfma_f32_16x16x32_bf16 v[28:31], v[28:31], v[20:23], 0
	s_waitcnt lgkmcnt(3)
	v_mfma_f32_16x16x32_bf16 v[102:105], v[94:97], v[4:7], 0
	s_waitcnt lgkmcnt(1)
	v_mfma_f32_16x16x32_bf16 v[4:7], v[106:109], v[4:7], 0
	v_mfma_f32_16x16x32_bf16 v[16:19], v[12:15], v[8:11], v[16:19]
	v_mfma_f32_16x16x32_bf16 v[0:3], v[12:15], v[24:27], v[0:3]
	v_mfma_f32_16x16x32_bf16 v[12:15], v[86:89], v[8:11], v[90:93]
	v_mfma_f32_16x16x32_bf16 v[28:31], v[86:89], v[24:27], v[28:31]
	v_mfma_f32_16x16x32_bf16 v[86:89], v[98:101], v[8:11], v[102:105]
	s_waitcnt lgkmcnt(0)
	v_mfma_f32_16x16x32_bf16 v[4:7], v[110:113], v[8:11], v[4:7]
	ds_read_b128 v[8:11], v83 offset:128
	v_mfma_f32_16x16x32_bf16 v[94:97], v[94:97], v[20:23], 0
	v_mfma_f32_16x16x32_bf16 v[20:23], v[106:109], v[20:23], 0
	v_mfma_f32_16x16x32_bf16 v[90:93], v[98:101], v[24:27], v[94:97]
	v_mfma_f32_16x16x32_bf16 v[20:23], v[110:113], v[24:27], v[20:23]
	ds_read_b128 v[24:27], v82 offset:128
	s_nop 3
	ds_read_b128 v[94:97], v82 offset:192
	ds_read_b128 v[98:101], v83 offset:192
	ds_read_b128 v[102:105], v82 offset:4480
	ds_read_b128 v[106:109], v82 offset:4544
	s_waitcnt lgkmcnt(4)
	v_mfma_f32_16x16x32_bf16 v[16:19], v[8:11], v[24:27], v[16:19]
	s_waitcnt lgkmcnt(1)
	v_mfma_f32_16x16x32_bf16 v[0:3], v[8:11], v[102:105], v[0:3]
	ds_read_b128 v[8:11], v83 offset:4480
	ds_read_b128 v[110:113], v83 offset:4544
	s_waitcnt lgkmcnt(1)
	v_mfma_f32_16x16x32_bf16 v[12:15], v[8:11], v[24:27], v[12:15]
	v_mfma_f32_16x16x32_bf16 v[8:11], v[8:11], v[102:105], v[28:31]
	s_nop 2
	ds_read_b128 v[28:31], v83 offset:8832
	ds_read_b128 v[114:117], v83 offset:8896
	s_waitcnt lgkmcnt(1)
	v_mfma_f32_16x16x32_bf16 v[86:89], v[28:31], v[24:27], v[86:89]
	v_mfma_f32_16x16x32_bf16 v[90:93], v[28:31], v[102:105], v[90:93]
	ds_read_b128 v[28:31], v83 offset:13184
	ds_read_b128 v[118:121], v83 offset:13248
	s_waitcnt lgkmcnt(0)
	s_barrier
	v_mfma_f32_16x16x32_bf16 v[4:7], v[28:31], v[24:27], v[4:7]
	v_mfma_f32_16x16x32_bf16 v[102:105], v[28:31], v[102:105], v[20:23]
	v_mfma_f32_16x16x32_bf16 v[28:31], v[98:101], v[106:109], v[0:3]
	v_mfma_f32_16x16x32_bf16 v[24:27], v[98:101], v[94:97], v[16:19]
	v_mfma_f32_16x16x32_bf16 v[20:23], v[110:113], v[106:109], v[8:11]
	v_mfma_f32_16x16x32_bf16 v[8:11], v[114:117], v[94:97], v[86:89]
	s_nop 4
	v_mul_f32_e32 v87, 0x3db504f3, v28
	v_mul_f32_e32 v86, 0x3db504f3, v24
	v_mul_f32_e32 v0, v87, v87
	v_fmac_f32_e32 v0, v86, v86
	v_mfma_f32_16x16x32_bf16 v[16:19], v[110:113], v[94:97], v[12:15]
	ds_write2_b32 v54, v86, v87 offset1:16
	v_add_f32_dpp v24, v0, v0 quad_perm:[1,0,3,2] row_mask:0xf bank_mask:0xf bound_ctrl:1
	v_mfma_f32_16x16x32_bf16 v[0:3], v[118:121], v[94:97], v[4:7]
	s_nop 2
	v_add_f32_dpp v4, v24, v24 quad_perm:[2,3,0,1] row_mask:0xf bank_mask:0xf bound_ctrl:1
	v_mfma_f32_16x16x32_bf16 v[12:15], v[114:117], v[106:109], v[90:93]
	s_nop 0
	v_add_f32_dpp v24, v4, v4 row_half_mirror row_mask:0xf bank_mask:0xf bound_ctrl:1
	v_mfma_f32_16x16x32_bf16 v[4:7], v[118:121], v[106:109], v[102:105]
	s_nop 0
	v_mov_b32_dpp v28, v24 row_mirror row_mask:0xf bank_mask:0xf bound_ctrl:1
	s_and_saveexec_b64 s[10:11], vcc
	v_add_f32_e32 v24, v24, v28
	ds_write_b32 v55, v24
	s_or_b64 exec, exec, s[10:11]
	v_mul_f32_e32 v29, 0x3db504f3, v29
	v_mul_f32_e32 v28, 0x3db504f3, v25
	v_mul_f32_e32 v24, v29, v29
	v_fmac_f32_e32 v24, v28, v28
	ds_write2_b32 v56, v28, v29 offset1:16
	s_nop 0
	v_add_f32_dpp v24, v24, v24 quad_perm:[1,0,3,2] row_mask:0xf bank_mask:0xf bound_ctrl:1
	s_nop 1
	v_add_f32_dpp v24, v24, v24 quad_perm:[2,3,0,1] row_mask:0xf bank_mask:0xf bound_ctrl:1
	s_nop 1
	v_add_f32_dpp v24, v24, v24 row_half_mirror row_mask:0xf bank_mask:0xf bound_ctrl:1
	s_nop 1
	v_mov_b32_dpp v25, v24 row_mirror row_mask:0xf bank_mask:0xf bound_ctrl:1
	s_and_saveexec_b64 s[10:11], vcc
	v_add_f32_e32 v24, v24, v25
	ds_write_b32 v55, v24 offset:4
	s_or_b64 exec, exec, s[10:11]
	v_mul_f32_e32 v28, 0x3db504f3, v30
	v_mul_f32_e32 v26, 0x3db504f3, v26
	v_mul_f32_e32 v24, v28, v28
	v_fmac_f32_e32 v24, v26, v26
	ds_write2_b32 v57, v26, v28 offset1:16
	s_nop 0
	v_add_f32_dpp v24, v24, v24 quad_perm:[1,0,3,2] row_mask:0xf bank_mask:0xf bound_ctrl:1
	s_nop 1
	v_add_f32_dpp v24, v24, v24 quad_perm:[2,3,0,1] row_mask:0xf bank_mask:0xf bound_ctrl:1
	s_nop 1
	v_add_f32_dpp v24, v24, v24 row_half_mirror row_mask:0xf bank_mask:0xf bound_ctrl:1
	s_nop 1
	v_mov_b32_dpp v25, v24 row_mirror row_mask:0xf bank_mask:0xf bound_ctrl:1
	s_and_saveexec_b64 s[10:11], vcc
	v_add_f32_e32 v24, v24, v25
	ds_write_b32 v55, v24 offset:8
	s_or_b64 exec, exec, s[10:11]
	v_mul_f32_e32 v26, 0x3db504f3, v27
	v_mul_f32_e32 v27, 0x3db504f3, v31
	v_mul_f32_e32 v24, v27, v27
	v_fmac_f32_e32 v24, v26, v26
	ds_write2_b32 v58, v26, v27 offset1:16
	s_nop 0
	v_add_f32_dpp v24, v24, v24 quad_perm:[1,0,3,2] row_mask:0xf bank_mask:0xf bound_ctrl:1
	s_nop 1
	v_add_f32_dpp v24, v24, v24 quad_perm:[2,3,0,1] row_mask:0xf bank_mask:0xf bound_ctrl:1
	s_nop 1
	v_add_f32_dpp v24, v24, v24 row_half_mirror row_mask:0xf bank_mask:0xf bound_ctrl:1
	s_nop 1
	v_mov_b32_dpp v25, v24 row_mirror row_mask:0xf bank_mask:0xf bound_ctrl:1
	s_and_saveexec_b64 s[10:11], vcc
	v_add_f32_e32 v24, v24, v25
	ds_write_b32 v59, v24
	s_or_b64 exec, exec, s[10:11]
	v_mul_f32_e32 v25, 0x3db504f3, v20
	v_mul_f32_e32 v24, 0x3db504f3, v16
	v_mul_f32_e32 v16, v25, v25
	v_fmac_f32_e32 v16, v24, v24
	ds_write2_b32 v60, v24, v25 offset1:16
	s_nop 0
	v_add_f32_dpp v16, v16, v16 quad_perm:[1,0,3,2] row_mask:0xf bank_mask:0xf bound_ctrl:1
	s_nop 1
	v_add_f32_dpp v16, v16, v16 quad_perm:[2,3,0,1] row_mask:0xf bank_mask:0xf bound_ctrl:1
	s_nop 1
	v_add_f32_dpp v16, v16, v16 row_half_mirror row_mask:0xf bank_mask:0xf bound_ctrl:1
	s_nop 1
	v_mov_b32_dpp v20, v16 row_mirror row_mask:0xf bank_mask:0xf bound_ctrl:1
	s_and_saveexec_b64 s[10:11], vcc
	v_add_f32_e32 v16, v16, v20
	ds_write_b32 v55, v16 offset:64
	s_or_b64 exec, exec, s[10:11]
	v_mul_f32_e32 v21, 0x3db504f3, v21
	v_mul_f32_e32 v20, 0x3db504f3, v17
	v_mul_f32_e32 v16, v21, v21
	v_fmac_f32_e32 v16, v20, v20
	ds_write2_b32 v61, v20, v21 offset1:16
	s_nop 0
	v_add_f32_dpp v16, v16, v16 quad_perm:[1,0,3,2] row_mask:0xf bank_mask:0xf bound_ctrl:1
	s_nop 1
	v_add_f32_dpp v16, v16, v16 quad_perm:[2,3,0,1] row_mask:0xf bank_mask:0xf bound_ctrl:1
	s_nop 1
	v_add_f32_dpp v16, v16, v16 row_half_mirror row_mask:0xf bank_mask:0xf bound_ctrl:1
	s_nop 1
	v_mov_b32_dpp v17, v16 row_mirror row_mask:0xf bank_mask:0xf bound_ctrl:1
	s_and_saveexec_b64 s[10:11], vcc
	v_add_f32_e32 v16, v16, v17
	ds_write_b32 v55, v16 offset:68
	s_or_b64 exec, exec, s[10:11]
	v_mul_f32_e32 v20, 0x3db504f3, v22
	v_mul_f32_e32 v18, 0x3db504f3, v18
	v_mul_f32_e32 v16, v20, v20
	v_fmac_f32_e32 v16, v18, v18
	ds_write2_b32 v62, v18, v20 offset1:16
	s_nop 0
	v_add_f32_dpp v16, v16, v16 quad_perm:[1,0,3,2] row_mask:0xf bank_mask:0xf bound_ctrl:1
	s_nop 1
	v_add_f32_dpp v16, v16, v16 quad_perm:[2,3,0,1] row_mask:0xf bank_mask:0xf bound_ctrl:1
	s_nop 1
	v_add_f32_dpp v16, v16, v16 row_half_mirror row_mask:0xf bank_mask:0xf bound_ctrl:1
	s_nop 1
	v_mov_b32_dpp v17, v16 row_mirror row_mask:0xf bank_mask:0xf bound_ctrl:1
	s_and_saveexec_b64 s[10:11], vcc
	v_add_f32_e32 v16, v16, v17
	ds_write_b32 v55, v16 offset:72
	s_or_b64 exec, exec, s[10:11]
	v_mul_f32_e32 v18, 0x3db504f3, v19
	v_mul_f32_e32 v19, 0x3db504f3, v23
	v_mul_f32_e32 v16, v19, v19
	v_fmac_f32_e32 v16, v18, v18
	ds_write2_b32 v63, v18, v19 offset1:16
	s_nop 0
	v_add_f32_dpp v16, v16, v16 quad_perm:[1,0,3,2] row_mask:0xf bank_mask:0xf bound_ctrl:1
	s_nop 1
	v_add_f32_dpp v16, v16, v16 quad_perm:[2,3,0,1] row_mask:0xf bank_mask:0xf bound_ctrl:1
	s_nop 1
	v_add_f32_dpp v16, v16, v16 row_half_mirror row_mask:0xf bank_mask:0xf bound_ctrl:1
	s_nop 1
	v_mov_b32_dpp v17, v16 row_mirror row_mask:0xf bank_mask:0xf bound_ctrl:1
	s_and_saveexec_b64 s[10:11], vcc
	v_add_f32_e32 v16, v16, v17
	ds_write_b32 v64, v16
	s_or_b64 exec, exec, s[10:11]
	v_mul_f32_e32 v17, 0x3db504f3, v12
	v_mul_f32_e32 v16, 0x3db504f3, v8
	v_mul_f32_e32 v8, v17, v17
	v_fmac_f32_e32 v8, v16, v16
	ds_write2_b32 v65, v16, v17 offset1:16
	s_nop 0
	v_add_f32_dpp v8, v8, v8 quad_perm:[1,0,3,2] row_mask:0xf bank_mask:0xf bound_ctrl:1
	s_nop 1
	v_add_f32_dpp v8, v8, v8 quad_perm:[2,3,0,1] row_mask:0xf bank_mask:0xf bound_ctrl:1
	s_nop 1
	v_add_f32_dpp v8, v8, v8 row_half_mirror row_mask:0xf bank_mask:0xf bound_ctrl:1
	s_nop 1
	v_mov_b32_dpp v12, v8 row_mirror row_mask:0xf bank_mask:0xf bound_ctrl:1
	s_and_saveexec_b64 s[10:11], vcc
	v_add_f32_e32 v8, v8, v12
	ds_write_b32 v55, v8 offset:128
	s_or_b64 exec, exec, s[10:11]
	v_mul_f32_e32 v13, 0x3db504f3, v13
	v_mul_f32_e32 v12, 0x3db504f3, v9
	v_mul_f32_e32 v8, v13, v13
	v_fmac_f32_e32 v8, v12, v12
	ds_write2_b32 v66, v12, v13 offset1:16
	s_nop 0
	v_add_f32_dpp v8, v8, v8 quad_perm:[1,0,3,2] row_mask:0xf bank_mask:0xf bound_ctrl:1
	s_nop 1
	v_add_f32_dpp v8, v8, v8 quad_perm:[2,3,0,1] row_mask:0xf bank_mask:0xf bound_ctrl:1
	s_nop 1
	v_add_f32_dpp v8, v8, v8 row_half_mirror row_mask:0xf bank_mask:0xf bound_ctrl:1
	s_nop 1
	v_mov_b32_dpp v9, v8 row_mirror row_mask:0xf bank_mask:0xf bound_ctrl:1
	s_and_saveexec_b64 s[10:11], vcc
	v_add_f32_e32 v8, v8, v9
	ds_write_b32 v55, v8 offset:132
	s_or_b64 exec, exec, s[10:11]
	v_mul_f32_e32 v12, 0x3db504f3, v14
	v_mul_f32_e32 v10, 0x3db504f3, v10
	v_mul_f32_e32 v8, v12, v12
	v_fmac_f32_e32 v8, v10, v10
	ds_write2_b32 v67, v10, v12 offset1:16
	s_nop 0
	v_add_f32_dpp v8, v8, v8 quad_perm:[1,0,3,2] row_mask:0xf bank_mask:0xf bound_ctrl:1
	s_nop 1
	v_add_f32_dpp v8, v8, v8 quad_perm:[2,3,0,1] row_mask:0xf bank_mask:0xf bound_ctrl:1
	s_nop 1
	v_add_f32_dpp v8, v8, v8 row_half_mirror row_mask:0xf bank_mask:0xf bound_ctrl:1
	s_nop 1
	v_mov_b32_dpp v9, v8 row_mirror row_mask:0xf bank_mask:0xf bound_ctrl:1
	s_and_saveexec_b64 s[10:11], vcc
	v_add_f32_e32 v8, v8, v9
	ds_write_b32 v55, v8 offset:136
	s_or_b64 exec, exec, s[10:11]
	v_mul_f32_e32 v10, 0x3db504f3, v11
	v_mul_f32_e32 v11, 0x3db504f3, v15
	v_mul_f32_e32 v8, v11, v11
	v_fmac_f32_e32 v8, v10, v10
	ds_write2_b32 v68, v10, v11 offset1:16
	s_nop 0
	v_add_f32_dpp v8, v8, v8 quad_perm:[1,0,3,2] row_mask:0xf bank_mask:0xf bound_ctrl:1
	s_nop 1
	v_add_f32_dpp v8, v8, v8 quad_perm:[2,3,0,1] row_mask:0xf bank_mask:0xf bound_ctrl:1
	s_nop 1
	v_add_f32_dpp v8, v8, v8 row_half_mirror row_mask:0xf bank_mask:0xf bound_ctrl:1
	s_nop 1
	v_mov_b32_dpp v9, v8 row_mirror row_mask:0xf bank_mask:0xf bound_ctrl:1
	s_and_saveexec_b64 s[10:11], vcc
	v_add_f32_e32 v8, v8, v9
	ds_write_b32 v69, v8
	s_or_b64 exec, exec, s[10:11]
	v_mul_f32_e32 v9, 0x3db504f3, v4
	v_mul_f32_e32 v8, 0x3db504f3, v0
	v_mul_f32_e32 v0, v9, v9
	v_fmac_f32_e32 v0, v8, v8
	ds_write2_b32 v70, v8, v9 offset1:16
	s_nop 0
	v_add_f32_dpp v0, v0, v0 quad_perm:[1,0,3,2] row_mask:0xf bank_mask:0xf bound_ctrl:1
	s_nop 1
	v_add_f32_dpp v0, v0, v0 quad_perm:[2,3,0,1] row_mask:0xf bank_mask:0xf bound_ctrl:1
	s_nop 1
	v_add_f32_dpp v0, v0, v0 row_half_mirror row_mask:0xf bank_mask:0xf bound_ctrl:1
	s_nop 1
	v_mov_b32_dpp v4, v0 row_mirror row_mask:0xf bank_mask:0xf bound_ctrl:1
	s_and_saveexec_b64 s[10:11], vcc
	v_add_f32_e32 v0, v0, v4
	ds_write_b32 v55, v0 offset:192
	s_or_b64 exec, exec, s[10:11]
	v_mul_f32_e32 v5, 0x3db504f3, v5
	v_mul_f32_e32 v4, 0x3db504f3, v1
	v_mul_f32_e32 v0, v5, v5
	v_fmac_f32_e32 v0, v4, v4
	ds_write2_b32 v71, v4, v5 offset1:16
	s_nop 0
	v_add_f32_dpp v0, v0, v0 quad_perm:[1,0,3,2] row_mask:0xf bank_mask:0xf bound_ctrl:1
	s_nop 1
	v_add_f32_dpp v0, v0, v0 quad_perm:[2,3,0,1] row_mask:0xf bank_mask:0xf bound_ctrl:1
	s_nop 1
	v_add_f32_dpp v0, v0, v0 row_half_mirror row_mask:0xf bank_mask:0xf bound_ctrl:1
	s_nop 1
	v_mov_b32_dpp v1, v0 row_mirror row_mask:0xf bank_mask:0xf bound_ctrl:1
	s_and_saveexec_b64 s[10:11], vcc
	v_add_f32_e32 v0, v0, v1
	ds_write_b32 v55, v0 offset:196
	s_or_b64 exec, exec, s[10:11]
	v_mul_f32_e32 v4, 0x3db504f3, v6
	v_mul_f32_e32 v2, 0x3db504f3, v2
	v_mul_f32_e32 v0, v4, v4
	v_fmac_f32_e32 v0, v2, v2
	ds_write2_b32 v72, v2, v4 offset1:16
	s_nop 0
	v_add_f32_dpp v0, v0, v0 quad_perm:[1,0,3,2] row_mask:0xf bank_mask:0xf bound_ctrl:1
	s_nop 1
	v_add_f32_dpp v0, v0, v0 quad_perm:[2,3,0,1] row_mask:0xf bank_mask:0xf bound_ctrl:1
	s_nop 1
	v_add_f32_dpp v0, v0, v0 row_half_mirror row_mask:0xf bank_mask:0xf bound_ctrl:1
	s_nop 1
	v_mov_b32_dpp v1, v0 row_mirror row_mask:0xf bank_mask:0xf bound_ctrl:1
	s_and_saveexec_b64 s[10:11], vcc
	v_add_f32_e32 v0, v0, v1
	ds_write_b32 v55, v0 offset:200
	s_or_b64 exec, exec, s[10:11]
	v_mul_f32_e32 v2, 0x3db504f3, v3
	v_mul_f32_e32 v3, 0x3db504f3, v7
	v_mul_f32_e32 v0, v3, v3
	v_fmac_f32_e32 v0, v2, v2
	ds_write2_b32 v73, v2, v3 offset1:16
	s_nop 0
	v_add_f32_dpp v0, v0, v0 quad_perm:[1,0,3,2] row_mask:0xf bank_mask:0xf bound_ctrl:1
	s_nop 1
	v_add_f32_dpp v0, v0, v0 quad_perm:[2,3,0,1] row_mask:0xf bank_mask:0xf bound_ctrl:1
	s_nop 1
	v_add_f32_dpp v0, v0, v0 row_half_mirror row_mask:0xf bank_mask:0xf bound_ctrl:1
	s_nop 1
	v_mov_b32_dpp v1, v0 row_mirror row_mask:0xf bank_mask:0xf bound_ctrl:1
	s_and_saveexec_b64 s[10:11], vcc
	s_cbranch_execz .LBB0_839
	v_add_f32_e32 v0, v0, v1
	ds_write_b32 v74, v0
	s_branch .LBB0_839
